# transposer as one software pipeline across all nine tensors: no pipeline drain at tensor switches, pointers preloaded
# speedup vs baseline: 1.0037x; 1.0037x over previous
; #define LAS __attribute__((address_space(3)))
; __device__ __forceinline__ void transpose_tensor(const float* W, const float* g, int gstep, int nl, int K, int N, bf16* WT, LAS float* scr, int gw, int NGW, int lane) {
;     const int nblk = N / 32, per = (K / 64) * nblk, total = nl * per;
;     for (int it = gw; it < total; it += NGW) { const int l = it / per, r = it - l * per;
;         transpose_item(W + (size_t)l * K * N, g ? g + (size_t)l * gstep : nullptr, K, N, WT + (size_t)l * K * N, scr, r / nblk, r % nblk, lane); }
; __global__ void __launch_bounds__(NWAVES * 64, 2) fwd(Args args) {
;     ...
;         transpose_tensor(ka->in[8], ka->in[4], 2 * DM, 2, DM, NQKV, WSB(WS_WQKVA), scr, gw, NGW, lane);
;         transpose_tensor(ka->in[13], ka->in[4] + DM, 2 * DM, 2, DM, 3 * NQKV, WSB(WS_WQKVB), scr, gw, NGW, lane);
;         transpose_tensor(ka->in[12], nullptr, 0, 2, DM, DM, WSB(WS_WOA), scr, gw, NGW, lane);
;         transpose_tensor(ka->in[17], nullptr, 0, 2, DM, DM, WSB(WS_WOB), scr, gw, NGW, lane);
;         transpose_tensor(ka->in[18], ka->in[5], DM, 4, DM, XHEAD * HD, WSB(WS_WQX), scr, gw, NGW, lane);
;         transpose_tensor(ka->in[19], nullptr, 0, 4, DM, 2 * XHEAD * HD, WSB(WS_WKVX), scr, gw, NGW, lane);
;         transpose_tensor(ka->in[22], nullptr, 0, 4, XHEAD * HD, DM, WSB(WS_WOX), scr, gw, NGW, lane);
;         transpose_tensor(ka->in[23], ka->in[7], DM, 4, DM, DFF, WSB(WS_WUP), scr, gw, NGW, lane);
;         transpose_tensor(ka->in[24], nullptr, 0, 4, DFF, DM, WSB(WS_WDN), scr, gw, NGW, lane);
.LBB0_13:
.LBB0_14:
	v_readlane_b32 s10, v252, 0
	v_readlane_b32 s11, v252, 1
	v_lshrrev_b32_e32 v100, 6, v0
	v_and_b32_e32 v101, 63, v0
	s_load_dwordx2 s[12:13], s[10:11], 0xd0
	s_load_dwordx2 s[66:67], s[10:11], 0x40
	s_load_dwordx2 s[68:69], s[10:11], 0x68
	s_load_dwordx2 s[70:71], s[10:11], 0x60
	s_load_dwordx2 s[72:73], s[10:11], 0x88
	s_load_dwordx2 s[74:75], s[10:11], 0x90
	s_load_dwordx2 s[76:77], s[10:11], 0x98
	s_load_dwordx2 s[78:79], s[10:11], 0xb0
	s_load_dwordx2 s[80:81], s[10:11], 0xb8
	s_load_dwordx2 s[82:83], s[10:11], 0xc0
	s_load_dwordx2 s[84:85], s[10:11], 0x20
	s_load_dwordx2 s[86:87], s[10:11], 0x28
	s_load_dwordx2 s[88:89], s[10:11], 0x38
	v_readfirstlane_b32 s14, v100
	v_lshrrev_b32_e32 v102, 5, v101
	v_and_b32_e32 v103, 31, v101
	v_and_b32_e32 v105, 7, v101
	v_lshrrev_b32_e32 v106, 3, v101
	s_lshl_b32 s15, s59, 3
	s_add_i32 s15, s15, s14
	s_lshl_b32 s16, s60, 3
	s_lshl_b32 s17, s14, 14
	v_mad_u32_u24 v104, v102, 33, v103
	v_lshl_add_u32 v104, v104, 2, s17
	v_mul_u32_u24_e32 v107, 0x108, v105
	v_add_u32_e32 v107, v107, v106
	v_lshl_add_u32 v107, v107, 2, s17
	v_lshlrev_b32_e32 v108, 5, v105
	v_lshlrev_b32_e32 v109, 2, v103
	v_lshlrev_b32_e32 v105, 4, v105
	s_mov_b32 s18, -1
	s_mov_b32 s24, 0
	s_mov_b32 s37, s15
	s_mov_b32 s65, 0
	s_waitcnt lgkmcnt(0)
.Lwt_adv:
	s_cmp_lt_u32 s37, s24
	s_cbranch_scc1 .Lwt_issue
	s_sub_u32 s37, s37, s24
	s_add_u32 s18, s18, 1
	s_cmp_ge_i32 s18, 9
	s_cbranch_scc1 .Lwt_none
	s_cmp_eq_u32 s18, 0
	s_cbranch_scc1 .Lwt_p0
	s_cmp_eq_u32 s18, 1
	s_cbranch_scc1 .Lwt_p1
	s_cmp_eq_u32 s18, 2
	s_cbranch_scc1 .Lwt_p2
	s_cmp_eq_u32 s18, 3
	s_cbranch_scc1 .Lwt_p3
	s_cmp_eq_u32 s18, 4
	s_cbranch_scc1 .Lwt_p4
	s_cmp_eq_u32 s18, 5
	s_cbranch_scc1 .Lwt_p5
	s_cmp_eq_u32 s18, 6
	s_cbranch_scc1 .Lwt_p6
	s_cmp_eq_u32 s18, 7
	s_cbranch_scc1 .Lwt_p7
	s_cmp_eq_u32 s18, 8
	s_cbranch_scc1 .Lwt_p8
	s_branch .Lwt_none
.Lwt_p0:
	s_mov_b64 s[38:39], s[66:67]
	s_mov_b32 s62, 0x800
	s_mov_b32 s63, 0x1800
	s_mov_b32 s64, 2
	s_mov_b32 s26, 0xaaaab
	s_mov_b32 s28, 0x1555556
	s_mov_b32 s34, 0x1000000
	s_mov_b64 s[40:41], s[84:85]
	s_mov_b32 s21, 0x0
	s_mov_b32 s22, 0x4000
	s_mov_b32 s23, 1
	s_branch .Lwt_derive
.Lwt_p1:
	s_mov_b64 s[38:39], s[68:69]
	s_mov_b32 s62, 0x800
	s_mov_b32 s63, 0x4800
	s_mov_b32 s64, 2
	s_mov_b32 s26, 0x38e39
	s_mov_b32 s28, 0x71c71d
	s_mov_b32 s34, 0x4000000
	s_mov_b64 s[40:41], s[84:85]
	s_mov_b32 s21, 0x2000
	s_mov_b32 s22, 0x4000
	s_mov_b32 s23, 1
	s_branch .Lwt_derive
.Lwt_p2:
	s_mov_b64 s[38:39], s[70:71]
	s_mov_b32 s62, 0x800
	s_mov_b32 s63, 0x800
	s_mov_b32 s64, 2
	s_mov_b32 s26, 0x200000
	s_mov_b32 s28, 0x4000000
	s_mov_b32 s34, 0xd000000
	s_mov_b64 s[40:41], s[84:85]
	s_mov_b32 s21, 0
	s_mov_b32 s22, 0
	s_mov_b32 s23, 0
	s_branch .Lwt_derive
.Lwt_p3:
	s_mov_b64 s[38:39], s[72:73]
	s_mov_b32 s62, 0x800
	s_mov_b32 s63, 0x800
	s_mov_b32 s64, 2
	s_mov_b32 s26, 0x200000
	s_mov_b32 s28, 0x4000000
	s_mov_b32 s34, 0xe000000
	s_mov_b64 s[40:41], s[84:85]
	s_mov_b32 s21, 0
	s_mov_b32 s22, 0
	s_mov_b32 s23, 0
	s_branch .Lwt_derive
.Lwt_p4:
	s_mov_b64 s[38:39], s[74:75]
	s_mov_b32 s62, 0x800
	s_mov_b32 s63, 0x200
	s_mov_b32 s64, 4
	s_mov_b32 s26, 0x800000
	s_mov_b32 s28, 0x10000000
	s_mov_b32 s34, 0xf000000
	s_mov_b64 s[40:41], s[86:87]
	s_mov_b32 s21, 0x0
	s_mov_b32 s22, 0x2000
	s_mov_b32 s23, 1
	s_branch .Lwt_derive
.Lwt_p5:
	s_mov_b64 s[38:39], s[76:77]
	s_mov_b32 s62, 0x800
	s_mov_b32 s63, 0x400
	s_mov_b32 s64, 4
	s_mov_b32 s26, 0x400000
	s_mov_b32 s28, 0x8000000
	s_mov_b32 s34, 0xf800000
	s_mov_b64 s[40:41], s[84:85]
	s_mov_b32 s21, 0
	s_mov_b32 s22, 0
	s_mov_b32 s23, 0
	s_branch .Lwt_derive
.Lwt_p6:
	s_mov_b64 s[38:39], s[78:79]
	s_mov_b32 s62, 0x200
	s_mov_b32 s63, 0x800
	s_mov_b32 s64, 4
	s_mov_b32 s26, 0x800000
	s_mov_b32 s28, 0x4000000
	s_mov_b32 s34, 0x10800000
	s_mov_b64 s[40:41], s[84:85]
	s_mov_b32 s21, 0
	s_mov_b32 s22, 0
	s_mov_b32 s23, 0
	s_branch .Lwt_derive
.Lwt_p7:
	s_mov_b64 s[38:39], s[80:81]
	s_mov_b32 s62, 0x800
	s_mov_b32 s63, 0x2000
	s_mov_b32 s64, 4
	s_mov_b32 s26, 0x80000
	s_mov_b32 s28, 0x1000000
	s_mov_b32 s34, 0x11000000
	s_mov_b64 s[40:41], s[88:89]
	s_mov_b32 s21, 0x0
	s_mov_b32 s22, 0x2000
	s_mov_b32 s23, 1
	s_branch .Lwt_derive
.Lwt_p8:
	s_mov_b64 s[38:39], s[82:83]
	s_mov_b32 s62, 0x2000
	s_mov_b32 s63, 0x800
	s_mov_b32 s64, 4
	s_mov_b32 s26, 0x80000
	s_mov_b32 s28, 0x4000000
	s_mov_b32 s34, 0x19000000
	s_mov_b64 s[40:41], s[84:85]
	s_mov_b32 s21, 0
	s_mov_b32 s22, 0
	s_mov_b32 s23, 0
	s_branch .Lwt_derive
.Lwt_derive:
	s_lshr_b32 s27, s63, 5
	s_lshr_b32 s25, s62, 6
	s_mul_i32 s25, s25, s27
	s_mul_i32 s24, s25, s64
	s_lshl_b32 s30, s63, 8
	s_mul_i32 s29, s62, s63
	s_lshl_b32 s31, s29, 1
	s_lshl_b32 s29, s29, 2
	s_lshl_b32 s32, s62, 6
	s_lshl_b32 s35, s63, 2
	s_lshl_b32 s36, s62, 1
	s_add_u32 s42, s12, s34
	s_addc_u32 s43, s13, 0
	s_add_u32 s40, s40, s21
	s_addc_u32 s41, s41, 0
	v_mad_u32_u24 v110, v102, s35, v109
	s_lshl_b32 s61, s35, 1
	v_add_u32_e32 v111, s61, v110
	v_add_u32_e32 v112, s61, v111
	v_add_u32_e32 v113, s61, v112
	v_add_u32_e32 v114, s61, v113
	v_add_u32_e32 v115, s61, v114
	v_add_u32_e32 v116, s61, v115
	v_add_u32_e32 v117, s61, v116
	v_add_u32_e32 v118, s61, v117
	v_add_u32_e32 v119, s61, v118
	v_add_u32_e32 v120, s61, v119
	v_add_u32_e32 v121, s61, v120
	v_add_u32_e32 v122, s61, v121
	v_add_u32_e32 v123, s61, v122
	v_add_u32_e32 v124, s61, v123
	v_add_u32_e32 v125, s61, v124
	v_add_u32_e32 v126, s61, v125
	v_add_u32_e32 v127, s61, v126
	v_add_u32_e32 v128, s61, v127
	v_add_u32_e32 v129, s61, v128
	v_add_u32_e32 v130, s61, v129
	v_add_u32_e32 v131, s61, v130
	v_add_u32_e32 v132, s61, v131
	v_add_u32_e32 v133, s61, v132
	v_add_u32_e32 v134, s61, v133
	v_add_u32_e32 v135, s61, v134
	v_add_u32_e32 v136, s61, v135
	v_add_u32_e32 v137, s61, v136
	v_add_u32_e32 v138, s61, v137
	v_add_u32_e32 v139, s61, v138
	v_add_u32_e32 v140, s61, v139
	v_add_u32_e32 v141, s61, v140
	v_mad_u32_u24 v142, v106, s36, v105
	s_lshl_b32 s61, s36, 3
	v_add_u32_e32 v143, s61, v142
	v_add_u32_e32 v144, s61, v143
	v_add_u32_e32 v145, s61, v144
	v_mov_b32_e32 v178, 1.0
	v_mov_b32_e32 v179, 1.0
	v_mov_b32_e32 v180, 1.0
	v_mov_b32_e32 v181, 1.0
	v_mov_b32_e32 v182, 1.0
	v_mov_b32_e32 v183, 1.0
	v_mov_b32_e32 v184, 1.0
	v_mov_b32_e32 v185, 1.0
	s_branch .Lwt_adv
; #define LAS __attribute__((address_space(3)))
; #define LDS_WAIT() asm volatile("s_waitcnt lgkmcnt(0)" ::: "memory")
; __device__ __forceinline__ void transpose_item(const float* W, const float* g  , int K, int N, bf16* WT, LAS float* scr, int kb, int nb, int lane) {
;     const int k0 = 64 * kb, n0 = 32 * nb;
; #pragma unroll 8
;     for (int i = 0; i < 32; ++i) { const int kk = 2 * i + (lane >> 5); const float gv = g ? g[k0 + kk] : 1.f; scr[kk * 33 + (lane & 31)] = W[(size_t)(k0 + kk) * N + n0 + (lane & 31)] * gv; }
;     LDS_WAIT(); asm volatile("" ::: "memory");
.Lwt_issue:
	s_mul_hi_u32 s54, s37, s26
	s_mul_i32 s55, s54, s25
	s_sub_u32 s55, s37, s55
	s_mul_hi_u32 s56, s55, s28
	s_mul_i32 s57, s56, s27
	s_sub_u32 s57, s55, s57
	s_mul_i32 s58, s54, s29
	s_mul_i32 s61, s56, s30
	s_add_u32 s58, s58, s61
	s_lshl_b32 s61, s57, 7
	s_add_u32 s58, s58, s61
	s_add_u32 s44, s38, s58
	s_addc_u32 s45, s39, 0
	s_mul_i32 s58, s54, s31
	s_mul_i32 s61, s57, s32
	s_add_u32 s58, s58, s61
	s_lshl_b32 s61, s56, 7
	s_add_u32 s58, s58, s61
	s_add_u32 s50, s42, s58
	s_addc_u32 s51, s43, 0
	s_mul_i32 s58, s54, s22
	s_lshl_b32 s61, s56, 8
	s_add_u32 s58, s58, s61
	s_add_u32 s48, s40, s58
	s_addc_u32 s49, s41, 0
	s_waitcnt lgkmcnt(0)
	global_load_dword v146, v110, s[44:45] nt
	global_load_dword v147, v111, s[44:45] nt
	global_load_dword v148, v112, s[44:45] nt
	global_load_dword v149, v113, s[44:45] nt
	global_load_dword v150, v114, s[44:45] nt
	global_load_dword v151, v115, s[44:45] nt
	global_load_dword v152, v116, s[44:45] nt
	global_load_dword v153, v117, s[44:45] nt
	global_load_dword v154, v118, s[44:45] nt
	global_load_dword v155, v119, s[44:45] nt
	global_load_dword v156, v120, s[44:45] nt
	global_load_dword v157, v121, s[44:45] nt
	global_load_dword v158, v122, s[44:45] nt
	global_load_dword v159, v123, s[44:45] nt
	global_load_dword v160, v124, s[44:45] nt
	global_load_dword v161, v125, s[44:45] nt
	global_load_dword v162, v126, s[44:45] nt
	global_load_dword v163, v127, s[44:45] nt
	global_load_dword v164, v128, s[44:45] nt
	global_load_dword v165, v129, s[44:45] nt
	global_load_dword v166, v130, s[44:45] nt
	global_load_dword v167, v131, s[44:45] nt
	global_load_dword v168, v132, s[44:45] nt
	global_load_dword v169, v133, s[44:45] nt
	global_load_dword v170, v134, s[44:45] nt
	global_load_dword v171, v135, s[44:45] nt
	global_load_dword v172, v136, s[44:45] nt
	global_load_dword v173, v137, s[44:45] nt
	global_load_dword v174, v138, s[44:45] nt
	global_load_dword v175, v139, s[44:45] nt
	global_load_dword v176, v140, s[44:45] nt
	global_load_dword v177, v141, s[44:45] nt
	s_cmp_eq_u32 s23, 0
	s_cbranch_scc1 .Lwt_nog
	global_load_dwordx4 v[178:181], v108, s[48:49]
	global_load_dwordx4 v[182:185], v108, s[48:49] offset:16
.Lwt_nog:
	s_mov_b32 s47, 1
	s_branch .Lwt_ret
.Lwt_none:
	s_mov_b32 s47, 0
.Lwt_ret:
	s_cmp_eq_u32 s65, 0
	s_cbranch_scc0 .Lwt_loopcont
	s_mov_b32 s65, 1
	s_cmp_eq_u32 s47, 0
	s_cbranch_scc1 .Lwt_end
	s_waitcnt vmcnt(0)
.Lwt_loop:
	v_mov_b32_e32 v186, v178
	v_mov_b32_e32 v187, v179
	v_mov_b32_e32 v188, v180
	v_mov_b32_e32 v189, v181
	v_mov_b32_e32 v190, v182
	v_mov_b32_e32 v191, v183
	v_mov_b32_e32 v192, v184
	v_mov_b32_e32 v193, v185
	v_mov_b32_e32 v242, v142
	v_mov_b32_e32 v243, v143
	v_mov_b32_e32 v244, v144
	v_mov_b32_e32 v245, v145
	ds_write_b32 v104, v146
	ds_write_b32 v104, v147 offset:264
	ds_write_b32 v104, v148 offset:528
	ds_write_b32 v104, v149 offset:792
	ds_write_b32 v104, v150 offset:1056
	ds_write_b32 v104, v151 offset:1320
	ds_write_b32 v104, v152 offset:1584
	ds_write_b32 v104, v153 offset:1848
	ds_write_b32 v104, v154 offset:2112
	ds_write_b32 v104, v155 offset:2376
	ds_write_b32 v104, v156 offset:2640
	ds_write_b32 v104, v157 offset:2904
	ds_write_b32 v104, v158 offset:3168
	ds_write_b32 v104, v159 offset:3432
	ds_write_b32 v104, v160 offset:3696
	ds_write_b32 v104, v161 offset:3960
	ds_write_b32 v104, v162 offset:4224
	ds_write_b32 v104, v163 offset:4488
	ds_write_b32 v104, v164 offset:4752
	ds_write_b32 v104, v165 offset:5016
	ds_write_b32 v104, v166 offset:5280
	ds_write_b32 v104, v167 offset:5544
	ds_write_b32 v104, v168 offset:5808
	ds_write_b32 v104, v169 offset:6072
	ds_write_b32 v104, v170 offset:6336
	ds_write_b32 v104, v171 offset:6600
	ds_write_b32 v104, v172 offset:6864
	ds_write_b32 v104, v173 offset:7128
	ds_write_b32 v104, v174 offset:7392
	ds_write_b32 v104, v175 offset:7656
	ds_write_b32 v104, v176 offset:7920
	ds_write_b32 v104, v177 offset:8184
	s_mov_b64 s[52:53], s[50:51]
	s_add_u32 s37, s37, s16
	s_branch .Lwt_adv
; #define GAS __attribute__((address_space(1)))
; #define LAS __attribute__((address_space(3)))
; #define LDS_WAIT() asm volatile("s_waitcnt lgkmcnt(0)" ::: "memory")
; __device__ __forceinline__ unsigned pk2(float lo, float hi) { return f2bf(lo) | (f2bf(hi) << 16); }
; __device__ __forceinline__ void transpose_item(const float* W, const float* g  , int K, int N, bf16* WT, LAS float* scr, int kb, int nb, int lane) {
;     ...
;     const int c = lane & 7;
; #pragma unroll
;     for (int j = 0; j < 4; ++j) { const int n = (lane >> 3) + 8 * j; const LAS float* s = scr + (8 * c) * 33 + n;
;         v4u o; o.x = pk2(s[0 * 33], s[1 * 33]); o.y = pk2(s[2 * 33], s[3 * 33]); o.z = pk2(s[4 * 33], s[5 * 33]); o.w = pk2(s[6 * 33], s[7 * 33]);
;         *(GAS v4u*)(WT + (size_t)(n0 + n) * K + k0 + 8 * c) = o; }
;     LDS_WAIT(); asm volatile("" ::: "memory");
.Lwt_loopcont:
	s_waitcnt lgkmcnt(0)
	ds_read2_b32 v[194:195], v107 offset0:0 offset1:33
	ds_read2_b32 v[196:197], v107 offset0:66 offset1:99
	ds_read2_b32 v[198:199], v107 offset0:132 offset1:165
	ds_read2_b32 v[200:201], v107 offset0:198 offset1:231
	ds_read2_b32 v[202:203], v107 offset0:8 offset1:41
	ds_read2_b32 v[204:205], v107 offset0:74 offset1:107
	ds_read2_b32 v[206:207], v107 offset0:140 offset1:173
	ds_read2_b32 v[208:209], v107 offset0:206 offset1:239
	ds_read2_b32 v[210:211], v107 offset0:16 offset1:49
	ds_read2_b32 v[212:213], v107 offset0:82 offset1:115
	ds_read2_b32 v[214:215], v107 offset0:148 offset1:181
	ds_read2_b32 v[216:217], v107 offset0:214 offset1:247
	ds_read2_b32 v[218:219], v107 offset0:24 offset1:57
	ds_read2_b32 v[220:221], v107 offset0:90 offset1:123
	ds_read2_b32 v[222:223], v107 offset0:156 offset1:189
	ds_read2_b32 v[224:225], v107 offset0:222 offset1:255
	s_waitcnt lgkmcnt(15)
	v_mul_f32_e32 v194, v186, v194
	v_mul_f32_e32 v195, v187, v195
	v_cvt_pk_bf16_f32 v226, v194, v195
	s_waitcnt lgkmcnt(14)
	v_mul_f32_e32 v196, v188, v196
	v_mul_f32_e32 v197, v189, v197
	v_cvt_pk_bf16_f32 v227, v196, v197
	s_waitcnt lgkmcnt(13)
	v_mul_f32_e32 v198, v190, v198
	v_mul_f32_e32 v199, v191, v199
	v_cvt_pk_bf16_f32 v228, v198, v199
	s_waitcnt lgkmcnt(12)
	v_mul_f32_e32 v200, v192, v200
	v_mul_f32_e32 v201, v193, v201
	v_cvt_pk_bf16_f32 v229, v200, v201
	global_store_dwordx4 v242, v[226:229], s[52:53]
	s_waitcnt lgkmcnt(11)
	v_mul_f32_e32 v202, v186, v202
	v_mul_f32_e32 v203, v187, v203
	v_cvt_pk_bf16_f32 v230, v202, v203
	s_waitcnt lgkmcnt(10)
	v_mul_f32_e32 v204, v188, v204
	v_mul_f32_e32 v205, v189, v205
	v_cvt_pk_bf16_f32 v231, v204, v205
	s_waitcnt lgkmcnt(9)
	v_mul_f32_e32 v206, v190, v206
	v_mul_f32_e32 v207, v191, v207
	v_cvt_pk_bf16_f32 v232, v206, v207
	s_waitcnt lgkmcnt(8)
	v_mul_f32_e32 v208, v192, v208
	v_mul_f32_e32 v209, v193, v209
	v_cvt_pk_bf16_f32 v233, v208, v209
	global_store_dwordx4 v243, v[230:233], s[52:53]
	s_waitcnt lgkmcnt(7)
	v_mul_f32_e32 v210, v186, v210
	v_mul_f32_e32 v211, v187, v211
	v_cvt_pk_bf16_f32 v234, v210, v211
	s_waitcnt lgkmcnt(6)
	v_mul_f32_e32 v212, v188, v212
	v_mul_f32_e32 v213, v189, v213
	v_cvt_pk_bf16_f32 v235, v212, v213
	s_waitcnt lgkmcnt(5)
	v_mul_f32_e32 v214, v190, v214
	v_mul_f32_e32 v215, v191, v215
	v_cvt_pk_bf16_f32 v236, v214, v215
	s_waitcnt lgkmcnt(4)
	v_mul_f32_e32 v216, v192, v216
	v_mul_f32_e32 v217, v193, v217
	v_cvt_pk_bf16_f32 v237, v216, v217
	global_store_dwordx4 v244, v[234:237], s[52:53]
	s_waitcnt lgkmcnt(3)
	v_mul_f32_e32 v218, v186, v218
	v_mul_f32_e32 v219, v187, v219
	v_cvt_pk_bf16_f32 v238, v218, v219
	s_waitcnt lgkmcnt(2)
	v_mul_f32_e32 v220, v188, v220
	v_mul_f32_e32 v221, v189, v221
	v_cvt_pk_bf16_f32 v239, v220, v221
	s_waitcnt lgkmcnt(1)
	v_mul_f32_e32 v222, v190, v222
	v_mul_f32_e32 v223, v191, v223
	v_cvt_pk_bf16_f32 v240, v222, v223
	s_waitcnt lgkmcnt(0)
	v_mul_f32_e32 v224, v192, v224
	v_mul_f32_e32 v225, v193, v225
	v_cvt_pk_bf16_f32 v241, v224, v225
	global_store_dwordx4 v245, v[238:241], s[52:53]
	s_cmp_eq_u32 s47, 0
	s_cbranch_scc1 .Lwt_end
	s_waitcnt vmcnt(4)
	s_branch .Lwt_loop
